# attention loop edge (7.12): row-max reduce and rescale compare moved ahead of the last P.V MFMA so only the branch follows it
# baseline (speedup 1.0000x reference)
; #define MFMA32(a, b, c) __builtin_amdgcn_mfma_f32_32x32x16_bf16((a), (b), (c), 0, 0, 0)
; DI float ex2(float x) { return __builtin_amdgcn_exp2f(x); }
; #define A_LOAD(KB) { _Pragma("unroll") for (int i = 0; i < 2; ++i) { rk[i] = *(const u32x4*)(kp + (size_t)((KB) * 64 + 32 * i) * 1024); rv[i] = *(const u32x4*)(vp + (size_t)(64 * i) * TOK + (KB) * 64); } }
; DI void attn_block(const Params& p, int layer, int hd, int q0, int nkeys, char* smem) {
;     ...
;   for (int kb = 0; kb < nkb; ++kb) {
;     const char* Vs = smem + c0 * ST + KT;
;     A_STORE(c2);
;     A_LOAD((kb + 3 < lastkb) ? kb + 3 : lastkb);
;     if (kb + 1 < nkb) A_SCORES(sn, c1);
;     float mx = fmaxf(sc[0][0], sc[1][0]);
; #pragma unroll
;     for (int i = 1; i < 16; ++i) mx = fmaxf(mx, fmaxf(sc[0][i], sc[1][i]));
;     {
;       const auto pr_ = __builtin_amdgcn_permlane32_swap(__float_as_uint(mx), __float_as_uint(mx), false, false);
;       mx = fmaxf(__uint_as_float(pr_[0]), __uint_as_float(pr_[1]));
;     }
;     if (__any(mx > m + 8.f)) {
;       const float mn = (mx > m + 8.f) ? mx : m;
;       const float alpha = ex2(m - mn);
;       l *= alpha;
; #pragma unroll
;       for (int vt = 0; vt < 4; ++vt)
; #pragma unroll
;         for (int i = 0; i < 16; ++i) o[vt][i] *= alpha;
;       m = mn;
;     }
;     bf16x8 va[2][4];
;     const char* vbase = Vs + r * VROW + 16 * h;
; #pragma unroll
;     for (int vt = 0; vt < 4; ++vt) va[0][vt] = *(const bf16x8*)(vbase + 32 * vt * VROW);
;     float ls[4] = {0.f, 0.f, 0.f, 0.f};
; #pragma unroll
;     for (int st = 0; st < 4; ++st) {
;       if (st < 3) {
; #pragma unroll
;         for (int vt = 0; vt < 4; ++vt) va[(st + 1) & 1][vt] = *(const bf16x8*)(vbase + 32 * vt * VROW + (st + 1) * 32);
;       }
;       float pv[8];
; #pragma unroll
;       for (int i = 0; i < 8; ++i) { pv[i] = ex2(sc[st >> 1][8 * (st & 1) + i] - m); ls[i & 3] += pv[i]; }
;       u32x4 pk; pk.x = pack2(pv[0], pv[1]); pk.y = pack2(pv[2], pv[3]); pk.z = pack2(pv[4], pv[5]); pk.w = pack2(pv[6], pv[7]);
;       const bf16x8 pb = __builtin_bit_cast(bf16x8, pk);
; #pragma unroll
;       for (int vt = 0; vt < 4; ++vt) o[vt] = MFMA32(va[st & 1][vt], pb, o[vt]);
;     }
;     l += (ls[0] + ls[1]) + (ls[2] + ls[3]);
.Lat_top_0:
	s_waitcnt lgkmcnt(5)
	v_mfma_f32_32x32x16_bf16 v[82:97], v[208:211], v[130:133], v[66:81]
	ds_read_b128 v[208:211], v206 offset:35936
	s_min_i32 s60, s6, 0x80
	s_add_i32 s60, s60, 3
	v_exp_f32_e32 v246, v114
	v_exp_f32_e32 v247, v115
	v_exp_f32_e32 v248, v116
	v_exp_f32_e32 v249, v117
	v_add_f32_e32 v197, v197, v246
	s_waitcnt lgkmcnt(4)
	v_mfma_f32_32x32x16_bf16 v[82:97], v[212:215], v[134:137], v[82:97]
	s_waitcnt vmcnt(3)
	ds_write_b128 v165, v[158:161] offset:0
	v_lshl_add_u32 v177, s60, 17, v175
	global_load_dwordx4 v[158:161], v177, s[52:53]
	v_add_f32_e32 v207, v207, v247
	v_cvt_pk_bf16_f32 v242, v246, v247
	v_exp_f32_e32 v250, v118
	v_add_f32_e32 v197, v197, v248
	v_add_f32_e32 v207, v207, v249
	s_waitcnt lgkmcnt(3)
	v_mfma_f32_32x32x16_bf16 v[82:97], v[216:219], v[138:141], v[82:97]
	v_cvt_pk_bf16_f32 v243, v248, v249
	v_exp_f32_e32 v251, v119
	v_exp_f32_e32 v237, v120
	v_add_f32_e32 v197, v197, v250
	v_exp_f32_e32 v196, v121
	s_waitcnt lgkmcnt(1)
	v_mfma_f32_32x32x16_bf16 v[82:97], v[208:211], v[142:145], v[82:97]
	v_add_f32_e32 v207, v207, v251
	v_cvt_pk_bf16_f32 v244, v250, v251
	v_cvt_pk_bf16_f32 v245, v237, v196
	v_add_f32_e32 v197, v197, v237
	v_add_f32_e32 v207, v207, v196
	v_mfma_f32_32x32x16_bf16 v[34:49], v[220:223], v[242:245], v[34:49]
	ds_read_b128 v[220:223], v163 offset:17440
	v_exp_f32_e32 v246, v122
	v_exp_f32_e32 v247, v123
	v_exp_f32_e32 v248, v124
	v_exp_f32_e32 v249, v125
	v_add_f32_e32 v197, v197, v246
	v_mfma_f32_32x32x16_bf16 v[18:33], v[224:227], v[242:245], v[18:33]
	ds_read_b128 v[224:227], v163 offset:22048
	s_waitcnt vmcnt(3)
	ds_write_b128 v165, v[154:157] offset:8704
	global_load_dwordx4 v[154:157], v177, s[54:55]
	v_add_f32_e32 v207, v207, v247
	v_cvt_pk_bf16_f32 v170, v246, v247
	v_exp_f32_e32 v250, v126
	v_add_f32_e32 v197, v197, v248
	v_add_f32_e32 v207, v207, v249
	v_mfma_f32_32x32x16_bf16 v[2:17], v[228:231], v[242:245], v[2:17]
	ds_read_b128 v[228:231], v163 offset:26656
	v_cvt_pk_bf16_f32 v171, v248, v249
	v_exp_f32_e32 v251, v127
	v_exp_f32_e32 v237, v128
	v_add_f32_e32 v197, v197, v250
	v_exp_f32_e32 v196, v129
	v_mfma_f32_32x32x16_bf16 v[50:65], v[238:241], v[242:245], v[50:65]
	ds_read_b128 v[238:241], v163 offset:31264
	v_add_f32_e32 v207, v207, v251
	v_cvt_pk_bf16_f32 v172, v250, v251
	v_cvt_pk_bf16_f32 v173, v237, v196
	v_add_f32_e32 v197, v197, v237
	v_add_f32_e32 v207, v207, v196
	s_waitcnt lgkmcnt(4)
	v_mfma_f32_32x32x16_bf16 v[34:49], v[220:223], v[170:173], v[34:49]
	ds_read_b128 v[220:223], v163 offset:17472
	v_exp_f32_e32 v246, v98
	v_exp_f32_e32 v247, v99
	v_exp_f32_e32 v248, v100
	v_exp_f32_e32 v249, v101
	v_add_f32_e32 v197, v197, v246
	s_waitcnt lgkmcnt(4)
	v_mfma_f32_32x32x16_bf16 v[18:33], v[224:227], v[170:173], v[18:33]
	ds_read_b128 v[224:227], v163 offset:22080
	s_waitcnt vmcnt(3)
	ds_write_b64 v174, v[146:147] offset:17408
	ds_write_b64 v174, v[148:149] offset:17424
	v_lshl_add_u32 v177, s60, 7, v176
	global_load_dwordx4 v[146:149], v177, s[56:57]
	v_add_f32_e32 v207, v207, v247
	v_cvt_pk_bf16_f32 v242, v246, v247
	v_exp_f32_e32 v250, v102
	v_add_f32_e32 v197, v197, v248
	v_add_f32_e32 v207, v207, v249
	s_waitcnt lgkmcnt(5)
	v_mfma_f32_32x32x16_bf16 v[2:17], v[228:231], v[170:173], v[2:17]
	ds_read_b128 v[228:231], v163 offset:26688
	v_cvt_pk_bf16_f32 v243, v248, v249
	v_exp_f32_e32 v251, v103
	v_exp_f32_e32 v237, v104
	v_add_f32_e32 v197, v197, v250
	v_exp_f32_e32 v196, v105
	s_waitcnt lgkmcnt(5)
	v_mfma_f32_32x32x16_bf16 v[50:65], v[238:241], v[170:173], v[50:65]
	ds_read_b128 v[238:241], v163 offset:31296
	v_add_f32_e32 v207, v207, v251
	v_cvt_pk_bf16_f32 v244, v250, v251
	v_cvt_pk_bf16_f32 v245, v237, v196
	v_add_f32_e32 v197, v197, v237
	v_add_f32_e32 v207, v207, v196
	s_waitcnt lgkmcnt(5)
	v_mfma_f32_32x32x16_bf16 v[34:49], v[220:223], v[242:245], v[34:49]
	ds_read_b128 v[220:223], v163 offset:17504
	ds_read_b128 v[212:215], v206 offset:44544
	v_exp_f32_e32 v246, v106
	v_exp_f32_e32 v247, v107
	v_exp_f32_e32 v248, v108
	v_exp_f32_e32 v249, v109
	v_add_f32_e32 v197, v197, v246
	s_waitcnt lgkmcnt(6)
	v_mfma_f32_32x32x16_bf16 v[18:33], v[224:227], v[242:245], v[18:33]
	ds_read_b128 v[224:227], v163 offset:22112
	s_waitcnt vmcnt(3)
	ds_write_b64 v174, v[150:151] offset:26624
	ds_write_b64 v174, v[152:153] offset:26640
	global_load_dwordx4 v[150:153], v177, s[58:59]
	ds_read_b128 v[216:219], v206 offset:44576
	v_add_f32_e32 v207, v207, v247
	v_cvt_pk_bf16_f32 v170, v246, v247
	v_exp_f32_e32 v250, v110
	v_add_f32_e32 v197, v197, v248
	v_add_f32_e32 v207, v207, v249
	s_waitcnt lgkmcnt(7)
	v_mfma_f32_32x32x16_bf16 v[2:17], v[228:231], v[242:245], v[2:17]
	ds_read_b128 v[228:231], v163 offset:26720
	ds_read_b128 v[208:211], v206 offset:44608
	v_cvt_pk_bf16_f32 v171, v248, v249
	v_exp_f32_e32 v251, v111
	v_exp_f32_e32 v237, v112
	v_add_f32_e32 v197, v197, v250
	v_exp_f32_e32 v196, v113
	s_waitcnt lgkmcnt(8)
	v_mfma_f32_32x32x16_bf16 v[50:65], v[238:241], v[242:245], v[50:65]
	ds_read_b128 v[238:241], v163 offset:31328
	v_add_f32_e32 v207, v207, v251
	v_cvt_pk_bf16_f32 v172, v250, v251
	v_cvt_pk_bf16_f32 v173, v237, v196
	v_add_f32_e32 v197, v197, v237
	v_add_f32_e32 v207, v207, v196
	s_waitcnt lgkmcnt(7)
	v_mfma_f32_32x32x16_bf16 v[114:129], v[212:215], v[130:133], v[66:81]
	ds_read_b128 v[212:215], v206 offset:44640
	v_max3_f32 v178, v82, v83, v84
	s_waitcnt lgkmcnt(4)
	v_mfma_f32_32x32x16_bf16 v[114:129], v[216:219], v[134:137], v[114:129]
	v_max3_f32 v179, v85, v86, v87
	s_waitcnt lgkmcnt(2)
	v_mfma_f32_32x32x16_bf16 v[114:129], v[208:211], v[138:141], v[114:129]
	v_max3_f32 v178, v178, v88, v89
	s_waitcnt lgkmcnt(0)
	v_mfma_f32_32x32x16_bf16 v[114:129], v[212:215], v[142:145], v[114:129]
	v_max3_f32 v179, v179, v90, v91
	s_waitcnt lgkmcnt(0)
	s_barrier
	v_mfma_f32_32x32x16_bf16 v[34:49], v[220:223], v[170:173], v[34:49]
	ds_read_b128 v[220:223], v164 offset:0
	ds_read_b128 v[208:211], v162 offset:0
	v_max3_f32 v178, v178, v92, v93
	v_max3_f32 v179, v179, v94, v95
	v_max3_f32 v178, v178, v96, v97
	v_mfma_f32_32x32x16_bf16 v[18:33], v[224:227], v[170:173], v[18:33]
	ds_read_b128 v[224:227], v164 offset:4608
	ds_read_b128 v[212:215], v162 offset:32
	v_max3_f32 v179, v179, v114, v115
	v_max3_f32 v178, v178, v116, v117
	v_max3_f32 v179, v179, v118, v119
	v_max3_f32 v178, v178, v120, v121
	v_mfma_f32_32x32x16_bf16 v[2:17], v[228:231], v[170:173], v[2:17]
	ds_read_b128 v[228:231], v164 offset:9216
	ds_read_b128 v[216:219], v162 offset:64
	v_max3_f32 v179, v179, v122, v123
	v_max3_f32 v178, v178, v124, v125
	v_max3_f32 v179, v179, v126, v127
	v_max3_f32 v178, v178, v128, v129
	v_max_f32_e32 v178, v178, v179
	v_mov_b32_e32 v179, v178
	s_nop 1
	v_permlane32_swap_b32_e32 v178, v179
	v_max_f32_e32 v178, v178, v179
	v_cmp_lt_f32_e32 vcc, 0x41000000, v178
	v_mfma_f32_32x32x16_bf16 v[50:65], v[238:241], v[170:173], v[50:65]
	ds_read_b128 v[238:241], v164 offset:13824
	s_cbranch_vccnz .Lat_rare_0

; #define MFMA32(a, b, c) __builtin_amdgcn_mfma_f32_32x32x16_bf16((a), (b), (c), 0, 0, 0)
; DI float ex2(float x) { return __builtin_amdgcn_exp2f(x); }
; #define A_LOAD(KB) { _Pragma("unroll") for (int i = 0; i < 2; ++i) { rk[i] = *(const u32x4*)(kp + (size_t)((KB) * 64 + 32 * i) * 1024); rv[i] = *(const u32x4*)(vp + (size_t)(64 * i) * TOK + (KB) * 64); } }
; DI void attn_block(const Params& p, int layer, int hd, int q0, int nkeys, char* smem) {
;     ...
;   for (int kb = 0; kb < nkb; ++kb) {
;     const char* Vs = smem + c0 * ST + KT;
;     A_STORE(c2);
;     A_LOAD((kb + 3 < lastkb) ? kb + 3 : lastkb);
;     if (kb + 1 < nkb) A_SCORES(sn, c1);
;     float mx = fmaxf(sc[0][0], sc[1][0]);
; #pragma unroll
;     for (int i = 1; i < 16; ++i) mx = fmaxf(mx, fmaxf(sc[0][i], sc[1][i]));
;     {
;       const auto pr_ = __builtin_amdgcn_permlane32_swap(__float_as_uint(mx), __float_as_uint(mx), false, false);
;       mx = fmaxf(__uint_as_float(pr_[0]), __uint_as_float(pr_[1]));
;     }
;     if (__any(mx > m + 8.f)) {
;       const float mn = (mx > m + 8.f) ? mx : m;
;       const float alpha = ex2(m - mn);
;       l *= alpha;
; #pragma unroll
;       for (int vt = 0; vt < 4; ++vt)
; #pragma unroll
;         for (int i = 0; i < 16; ++i) o[vt][i] *= alpha;
;       m = mn;
;     }
;     bf16x8 va[2][4];
;     const char* vbase = Vs + r * VROW + 16 * h;
; #pragma unroll
;     for (int vt = 0; vt < 4; ++vt) va[0][vt] = *(const bf16x8*)(vbase + 32 * vt * VROW);
;     float ls[4] = {0.f, 0.f, 0.f, 0.f};
; #pragma unroll
;     for (int st = 0; st < 4; ++st) {
;       if (st < 3) {
; #pragma unroll
;         for (int vt = 0; vt < 4; ++vt) va[(st + 1) & 1][vt] = *(const bf16x8*)(vbase + 32 * vt * VROW + (st + 1) * 32);
;       }
;       float pv[8];
; #pragma unroll
;       for (int i = 0; i < 8; ++i) { pv[i] = ex2(sc[st >> 1][8 * (st & 1) + i] - m); ls[i & 3] += pv[i]; }
;       u32x4 pk; pk.x = pack2(pv[0], pv[1]); pk.y = pack2(pv[2], pv[3]); pk.z = pack2(pv[4], pv[5]); pk.w = pack2(pv[6], pv[7]);
;       const bf16x8 pb = __builtin_bit_cast(bf16x8, pk);
; #pragma unroll
;       for (int vt = 0; vt < 4; ++vt) o[vt] = MFMA32(va[st & 1][vt], pb, o[vt]);
;     }
;     l += (ls[0] + ls[1]) + (ls[2] + ls[3]);
.Lat_top_1:
	s_waitcnt lgkmcnt(5)
	v_mfma_f32_32x32x16_bf16 v[98:113], v[208:211], v[130:133], v[66:81]
	ds_read_b128 v[208:211], v162 offset:96
	s_min_i32 s60, s6, 0x80
	s_add_i32 s60, s60, 3
	v_exp_f32_e32 v246, v82
	v_exp_f32_e32 v247, v83
	v_exp_f32_e32 v248, v84
	v_exp_f32_e32 v249, v85
	v_add_f32_e32 v197, v197, v246
	s_waitcnt lgkmcnt(4)
	v_mfma_f32_32x32x16_bf16 v[98:113], v[212:215], v[134:137], v[98:113]
	s_waitcnt vmcnt(3)
	ds_write_b128 v194, v[158:161] offset:16
	v_lshl_add_u32 v177, s60, 17, v175
	global_load_dwordx4 v[158:161], v177, s[52:53]
	v_add_f32_e32 v207, v207, v247
	v_cvt_pk_bf16_f32 v242, v246, v247
	v_exp_f32_e32 v250, v86
	v_add_f32_e32 v197, v197, v248
	v_add_f32_e32 v207, v207, v249
	s_waitcnt lgkmcnt(3)
	v_mfma_f32_32x32x16_bf16 v[98:113], v[216:219], v[138:141], v[98:113]
	v_cvt_pk_bf16_f32 v243, v248, v249
	v_exp_f32_e32 v251, v87
	v_exp_f32_e32 v237, v88
	v_add_f32_e32 v197, v197, v250
	v_exp_f32_e32 v196, v89
	s_waitcnt lgkmcnt(1)
	v_mfma_f32_32x32x16_bf16 v[98:113], v[208:211], v[142:145], v[98:113]
	v_add_f32_e32 v207, v207, v251
	v_cvt_pk_bf16_f32 v244, v250, v251
	v_cvt_pk_bf16_f32 v245, v237, v196
	v_add_f32_e32 v197, v197, v237
	v_add_f32_e32 v207, v207, v196
	v_mfma_f32_32x32x16_bf16 v[34:49], v[220:223], v[242:245], v[34:49]
	ds_read_b128 v[220:223], v164 offset:32
	v_exp_f32_e32 v246, v90
	v_exp_f32_e32 v247, v91
	v_exp_f32_e32 v248, v92
	v_exp_f32_e32 v249, v93
	v_add_f32_e32 v197, v197, v246
	v_mfma_f32_32x32x16_bf16 v[18:33], v[224:227], v[242:245], v[18:33]
	ds_read_b128 v[224:227], v164 offset:4640
	s_waitcnt vmcnt(3)
	ds_write_b128 v194, v[154:157] offset:8720
	global_load_dwordx4 v[154:157], v177, s[54:55]
	v_add_f32_e32 v207, v207, v247
	v_cvt_pk_bf16_f32 v170, v246, v247
	v_exp_f32_e32 v250, v94
	v_add_f32_e32 v197, v197, v248
	v_add_f32_e32 v207, v207, v249
	v_mfma_f32_32x32x16_bf16 v[2:17], v[228:231], v[242:245], v[2:17]
	ds_read_b128 v[228:231], v164 offset:9248
	v_cvt_pk_bf16_f32 v171, v248, v249
	v_exp_f32_e32 v251, v95
	v_exp_f32_e32 v237, v96
	v_add_f32_e32 v197, v197, v250
	v_exp_f32_e32 v196, v97
	v_mfma_f32_32x32x16_bf16 v[50:65], v[238:241], v[242:245], v[50:65]
	ds_read_b128 v[238:241], v164 offset:13856
	v_add_f32_e32 v207, v207, v251
	v_cvt_pk_bf16_f32 v172, v250, v251
	v_cvt_pk_bf16_f32 v173, v237, v196
	v_add_f32_e32 v197, v197, v237
	v_add_f32_e32 v207, v207, v196
	s_waitcnt lgkmcnt(4)
	v_mfma_f32_32x32x16_bf16 v[34:49], v[220:223], v[170:173], v[34:49]
	ds_read_b128 v[220:223], v164 offset:64
	v_exp_f32_e32 v246, v114
	v_exp_f32_e32 v247, v115
	v_exp_f32_e32 v248, v116
	v_exp_f32_e32 v249, v117
	v_add_f32_e32 v197, v197, v246
	s_waitcnt lgkmcnt(4)
	v_mfma_f32_32x32x16_bf16 v[18:33], v[224:227], v[170:173], v[18:33]
	ds_read_b128 v[224:227], v164 offset:4672
	s_waitcnt vmcnt(3)
	ds_write_b64 v205, v[146:147] offset:17424
	ds_write_b64 v205, v[148:149] offset:17440
	v_lshl_add_u32 v177, s60, 7, v176
	global_load_dwordx4 v[146:149], v177, s[56:57]
	v_add_f32_e32 v207, v207, v247
	v_cvt_pk_bf16_f32 v242, v246, v247
	v_exp_f32_e32 v250, v118
	v_add_f32_e32 v197, v197, v248
	v_add_f32_e32 v207, v207, v249
	s_waitcnt lgkmcnt(5)
	v_mfma_f32_32x32x16_bf16 v[2:17], v[228:231], v[170:173], v[2:17]
	ds_read_b128 v[228:231], v164 offset:9280
	v_cvt_pk_bf16_f32 v243, v248, v249
	v_exp_f32_e32 v251, v119
	v_exp_f32_e32 v237, v120
	v_add_f32_e32 v197, v197, v250
	v_exp_f32_e32 v196, v121
	s_waitcnt lgkmcnt(5)
	v_mfma_f32_32x32x16_bf16 v[50:65], v[238:241], v[170:173], v[50:65]
	ds_read_b128 v[238:241], v164 offset:13888
	v_add_f32_e32 v207, v207, v251
	v_cvt_pk_bf16_f32 v244, v250, v251
	v_cvt_pk_bf16_f32 v245, v237, v196
	v_add_f32_e32 v197, v197, v237
	v_add_f32_e32 v207, v207, v196
	s_waitcnt lgkmcnt(5)
	v_mfma_f32_32x32x16_bf16 v[34:49], v[220:223], v[242:245], v[34:49]
	ds_read_b128 v[220:223], v164 offset:96
	ds_read_b128 v[212:215], v162 offset:8704
	v_exp_f32_e32 v246, v122
	v_exp_f32_e32 v247, v123
	v_exp_f32_e32 v248, v124
	v_exp_f32_e32 v249, v125
	v_add_f32_e32 v197, v197, v246
	s_waitcnt lgkmcnt(6)
	v_mfma_f32_32x32x16_bf16 v[18:33], v[224:227], v[242:245], v[18:33]
	ds_read_b128 v[224:227], v164 offset:4704
	s_waitcnt vmcnt(3)
	ds_write_b64 v205, v[150:151] offset:26640
	ds_write_b64 v205, v[152:153] offset:26656
	global_load_dwordx4 v[150:153], v177, s[58:59]
	ds_read_b128 v[216:219], v162 offset:8736
	v_add_f32_e32 v207, v207, v247
	v_cvt_pk_bf16_f32 v170, v246, v247
	v_exp_f32_e32 v250, v126
	v_add_f32_e32 v197, v197, v248
	v_add_f32_e32 v207, v207, v249
	s_waitcnt lgkmcnt(7)
	v_mfma_f32_32x32x16_bf16 v[2:17], v[228:231], v[242:245], v[2:17]
	ds_read_b128 v[228:231], v164 offset:9312
	ds_read_b128 v[208:211], v162 offset:8768
	v_cvt_pk_bf16_f32 v171, v248, v249
	v_exp_f32_e32 v251, v127
	v_exp_f32_e32 v237, v128
	v_add_f32_e32 v197, v197, v250
	v_exp_f32_e32 v196, v129
	s_waitcnt lgkmcnt(8)
	v_mfma_f32_32x32x16_bf16 v[50:65], v[238:241], v[242:245], v[50:65]
	ds_read_b128 v[238:241], v164 offset:13920
	v_add_f32_e32 v207, v207, v251
	v_cvt_pk_bf16_f32 v172, v250, v251
	v_cvt_pk_bf16_f32 v173, v237, v196
	v_add_f32_e32 v197, v197, v237
	v_add_f32_e32 v207, v207, v196
	s_waitcnt lgkmcnt(7)
	v_mfma_f32_32x32x16_bf16 v[82:97], v[212:215], v[130:133], v[66:81]
	ds_read_b128 v[212:215], v162 offset:8800
	v_max3_f32 v178, v98, v99, v100
	s_waitcnt lgkmcnt(4)
	v_mfma_f32_32x32x16_bf16 v[82:97], v[216:219], v[134:137], v[82:97]
	v_max3_f32 v179, v101, v102, v103
	s_waitcnt lgkmcnt(2)
	v_mfma_f32_32x32x16_bf16 v[82:97], v[208:211], v[138:141], v[82:97]
	v_max3_f32 v178, v178, v104, v105
	s_waitcnt lgkmcnt(0)
	v_mfma_f32_32x32x16_bf16 v[82:97], v[212:215], v[142:145], v[82:97]
	v_max3_f32 v179, v179, v106, v107
	s_waitcnt lgkmcnt(0)
	s_barrier
	v_mfma_f32_32x32x16_bf16 v[34:49], v[220:223], v[170:173], v[34:49]
	ds_read_b128 v[220:223], v164 offset:35840
	ds_read_b128 v[208:211], v206 offset:0
	v_max3_f32 v178, v178, v108, v109
	v_max3_f32 v179, v179, v110, v111
	v_max3_f32 v178, v178, v112, v113
	v_mfma_f32_32x32x16_bf16 v[18:33], v[224:227], v[170:173], v[18:33]
	ds_read_b128 v[224:227], v164 offset:40448
	ds_read_b128 v[212:215], v206 offset:32
	v_max3_f32 v179, v179, v82, v83
	v_max3_f32 v178, v178, v84, v85
	v_max3_f32 v179, v179, v86, v87
	v_max3_f32 v178, v178, v88, v89
	v_mfma_f32_32x32x16_bf16 v[2:17], v[228:231], v[170:173], v[2:17]
	ds_read_b128 v[228:231], v164 offset:45056
	ds_read_b128 v[216:219], v206 offset:64
	v_max3_f32 v179, v179, v90, v91
	v_max3_f32 v178, v178, v92, v93
	v_max3_f32 v179, v179, v94, v95
	v_max3_f32 v178, v178, v96, v97
	v_max_f32_e32 v178, v178, v179
	v_mov_b32_e32 v179, v178
	s_nop 1
	v_permlane32_swap_b32_e32 v178, v179
	v_max_f32_e32 v178, v178, v179
	v_cmp_lt_f32_e32 vcc, 0x41000000, v178
	v_mfma_f32_32x32x16_bf16 v[50:65], v[238:241], v[170:173], v[50:65]
	ds_read_b128 v[238:241], v164 offset:49664
	s_cbranch_vccnz .Lat_rare_1

; #define MFMA32(a, b, c) __builtin_amdgcn_mfma_f32_32x32x16_bf16((a), (b), (c), 0, 0, 0)
; DI float ex2(float x) { return __builtin_amdgcn_exp2f(x); }
; #define A_LOAD(KB) { _Pragma("unroll") for (int i = 0; i < 2; ++i) { rk[i] = *(const u32x4*)(kp + (size_t)((KB) * 64 + 32 * i) * 1024); rv[i] = *(const u32x4*)(vp + (size_t)(64 * i) * TOK + (KB) * 64); } }
; DI void attn_block(const Params& p, int layer, int hd, int q0, int nkeys, char* smem) {
;     ...
;   for (int kb = 0; kb < nkb; ++kb) {
;     const char* Vs = smem + c0 * ST + KT;
;     A_STORE(c2);
;     A_LOAD((kb + 3 < lastkb) ? kb + 3 : lastkb);
;     if (kb + 1 < nkb) A_SCORES(sn, c1);
;     float mx = fmaxf(sc[0][0], sc[1][0]);
; #pragma unroll
;     for (int i = 1; i < 16; ++i) mx = fmaxf(mx, fmaxf(sc[0][i], sc[1][i]));
;     {
;       const auto pr_ = __builtin_amdgcn_permlane32_swap(__float_as_uint(mx), __float_as_uint(mx), false, false);
;       mx = fmaxf(__uint_as_float(pr_[0]), __uint_as_float(pr_[1]));
;     }
;     if (__any(mx > m + 8.f)) {
;       const float mn = (mx > m + 8.f) ? mx : m;
;       const float alpha = ex2(m - mn);
;       l *= alpha;
; #pragma unroll
;       for (int vt = 0; vt < 4; ++vt)
; #pragma unroll
;         for (int i = 0; i < 16; ++i) o[vt][i] *= alpha;
;       m = mn;
;     }
;     bf16x8 va[2][4];
;     const char* vbase = Vs + r * VROW + 16 * h;
; #pragma unroll
;     for (int vt = 0; vt < 4; ++vt) va[0][vt] = *(const bf16x8*)(vbase + 32 * vt * VROW);
;     float ls[4] = {0.f, 0.f, 0.f, 0.f};
; #pragma unroll
;     for (int st = 0; st < 4; ++st) {
;       if (st < 3) {
; #pragma unroll
;         for (int vt = 0; vt < 4; ++vt) va[(st + 1) & 1][vt] = *(const bf16x8*)(vbase + 32 * vt * VROW + (st + 1) * 32);
;       }
;       float pv[8];
; #pragma unroll
;       for (int i = 0; i < 8; ++i) { pv[i] = ex2(sc[st >> 1][8 * (st & 1) + i] - m); ls[i & 3] += pv[i]; }
;       u32x4 pk; pk.x = pack2(pv[0], pv[1]); pk.y = pack2(pv[2], pv[3]); pk.z = pack2(pv[4], pv[5]); pk.w = pack2(pv[6], pv[7]);
;       const bf16x8 pb = __builtin_bit_cast(bf16x8, pk);
; #pragma unroll
;       for (int vt = 0; vt < 4; ++vt) o[vt] = MFMA32(va[st & 1][vt], pb, o[vt]);
;     }
;     l += (ls[0] + ls[1]) + (ls[2] + ls[3]);
.Lat_top_2:
	s_waitcnt lgkmcnt(5)
	v_mfma_f32_32x32x16_bf16 v[114:129], v[208:211], v[130:133], v[66:81]
	ds_read_b128 v[208:211], v206 offset:96
	s_min_i32 s60, s6, 0x80
	s_add_i32 s60, s60, 3
	v_exp_f32_e32 v246, v98
	v_exp_f32_e32 v247, v99
	v_exp_f32_e32 v248, v100
	v_exp_f32_e32 v249, v101
	v_add_f32_e32 v197, v197, v246
	s_waitcnt lgkmcnt(4)
	v_mfma_f32_32x32x16_bf16 v[114:129], v[212:215], v[134:137], v[114:129]
	s_waitcnt vmcnt(3)
	ds_write_b128 v194, v[158:161] offset:35856
	v_lshl_add_u32 v177, s60, 17, v175
	global_load_dwordx4 v[158:161], v177, s[52:53]
	v_add_f32_e32 v207, v207, v247
	v_cvt_pk_bf16_f32 v242, v246, v247
	v_exp_f32_e32 v250, v102
	v_add_f32_e32 v197, v197, v248
	v_add_f32_e32 v207, v207, v249
	s_waitcnt lgkmcnt(3)
	v_mfma_f32_32x32x16_bf16 v[114:129], v[216:219], v[138:141], v[114:129]
	v_cvt_pk_bf16_f32 v243, v248, v249
	v_exp_f32_e32 v251, v103
	v_exp_f32_e32 v237, v104
	v_add_f32_e32 v197, v197, v250
	v_exp_f32_e32 v196, v105
	s_waitcnt lgkmcnt(1)
	v_mfma_f32_32x32x16_bf16 v[114:129], v[208:211], v[142:145], v[114:129]
	v_add_f32_e32 v207, v207, v251
	v_cvt_pk_bf16_f32 v244, v250, v251
	v_cvt_pk_bf16_f32 v245, v237, v196
	v_add_f32_e32 v197, v197, v237
	v_add_f32_e32 v207, v207, v196
	v_mfma_f32_32x32x16_bf16 v[34:49], v[220:223], v[242:245], v[34:49]
	ds_read_b128 v[220:223], v164 offset:35872
	v_exp_f32_e32 v246, v106
	v_exp_f32_e32 v247, v107
	v_exp_f32_e32 v248, v108
	v_exp_f32_e32 v249, v109
	v_add_f32_e32 v197, v197, v246
	v_mfma_f32_32x32x16_bf16 v[18:33], v[224:227], v[242:245], v[18:33]
	ds_read_b128 v[224:227], v164 offset:40480
	s_waitcnt vmcnt(3)
	ds_write_b128 v194, v[154:157] offset:44560
	global_load_dwordx4 v[154:157], v177, s[54:55]
	v_add_f32_e32 v207, v207, v247
	v_cvt_pk_bf16_f32 v170, v246, v247
	v_exp_f32_e32 v250, v110
	v_add_f32_e32 v197, v197, v248
	v_add_f32_e32 v207, v207, v249
	v_mfma_f32_32x32x16_bf16 v[2:17], v[228:231], v[242:245], v[2:17]
	ds_read_b128 v[228:231], v164 offset:45088
	v_cvt_pk_bf16_f32 v171, v248, v249
	v_exp_f32_e32 v251, v111
	v_exp_f32_e32 v237, v112
	v_add_f32_e32 v197, v197, v250
	v_exp_f32_e32 v196, v113
	v_mfma_f32_32x32x16_bf16 v[50:65], v[238:241], v[242:245], v[50:65]
	ds_read_b128 v[238:241], v164 offset:49696
	v_add_f32_e32 v207, v207, v251
	v_cvt_pk_bf16_f32 v172, v250, v251
	v_cvt_pk_bf16_f32 v173, v237, v196
	v_add_f32_e32 v197, v197, v237
	v_add_f32_e32 v207, v207, v196
	s_waitcnt lgkmcnt(4)
	v_mfma_f32_32x32x16_bf16 v[34:49], v[220:223], v[170:173], v[34:49]
	ds_read_b128 v[220:223], v164 offset:35904
	v_exp_f32_e32 v246, v82
	v_exp_f32_e32 v247, v83
	v_exp_f32_e32 v248, v84
	v_exp_f32_e32 v249, v85
	v_add_f32_e32 v197, v197, v246
	s_waitcnt lgkmcnt(4)
	v_mfma_f32_32x32x16_bf16 v[18:33], v[224:227], v[170:173], v[18:33]
	ds_read_b128 v[224:227], v164 offset:40512
	s_waitcnt vmcnt(3)
	ds_write_b64 v205, v[146:147] offset:53264
	ds_write_b64 v205, v[148:149] offset:53280
	v_lshl_add_u32 v177, s60, 7, v176
	global_load_dwordx4 v[146:149], v177, s[56:57]
	v_add_f32_e32 v207, v207, v247
	v_cvt_pk_bf16_f32 v242, v246, v247
	v_exp_f32_e32 v250, v86
	v_add_f32_e32 v197, v197, v248
	v_add_f32_e32 v207, v207, v249
	s_waitcnt lgkmcnt(5)
	v_mfma_f32_32x32x16_bf16 v[2:17], v[228:231], v[170:173], v[2:17]
	ds_read_b128 v[228:231], v164 offset:45120
	v_cvt_pk_bf16_f32 v243, v248, v249
	v_exp_f32_e32 v251, v87
	v_exp_f32_e32 v237, v88
	v_add_f32_e32 v197, v197, v250
	v_exp_f32_e32 v196, v89
	s_waitcnt lgkmcnt(5)
	v_mfma_f32_32x32x16_bf16 v[50:65], v[238:241], v[170:173], v[50:65]
	ds_read_b128 v[238:241], v164 offset:49728
	v_add_f32_e32 v207, v207, v251
	v_cvt_pk_bf16_f32 v244, v250, v251
	v_cvt_pk_bf16_f32 v245, v237, v196
	v_add_f32_e32 v197, v197, v237
	v_add_f32_e32 v207, v207, v196
	s_waitcnt lgkmcnt(5)
	v_mfma_f32_32x32x16_bf16 v[34:49], v[220:223], v[242:245], v[34:49]
	ds_read_b128 v[220:223], v164 offset:35936
	ds_read_b128 v[212:215], v206 offset:8704
	v_exp_f32_e32 v246, v90
	v_exp_f32_e32 v247, v91
	v_exp_f32_e32 v248, v92
	v_exp_f32_e32 v249, v93
	v_add_f32_e32 v197, v197, v246
	s_waitcnt lgkmcnt(6)
	v_mfma_f32_32x32x16_bf16 v[18:33], v[224:227], v[242:245], v[18:33]
	ds_read_b128 v[224:227], v164 offset:40544
	s_waitcnt vmcnt(3)
	ds_write_b64 v205, v[150:151] offset:62480
	ds_write_b64 v205, v[152:153] offset:62496
	global_load_dwordx4 v[150:153], v177, s[58:59]
	ds_read_b128 v[216:219], v206 offset:8736
	v_add_f32_e32 v207, v207, v247
	v_cvt_pk_bf16_f32 v170, v246, v247
	v_exp_f32_e32 v250, v94
	v_add_f32_e32 v197, v197, v248
	v_add_f32_e32 v207, v207, v249
	s_waitcnt lgkmcnt(7)
	v_mfma_f32_32x32x16_bf16 v[2:17], v[228:231], v[242:245], v[2:17]
	ds_read_b128 v[228:231], v164 offset:45152
	ds_read_b128 v[208:211], v206 offset:8768
	v_cvt_pk_bf16_f32 v171, v248, v249
	v_exp_f32_e32 v251, v95
	v_exp_f32_e32 v237, v96
	v_add_f32_e32 v197, v197, v250
	v_exp_f32_e32 v196, v97
	s_waitcnt lgkmcnt(8)
	v_mfma_f32_32x32x16_bf16 v[50:65], v[238:241], v[242:245], v[50:65]
	ds_read_b128 v[238:241], v164 offset:49760
	v_add_f32_e32 v207, v207, v251
	v_cvt_pk_bf16_f32 v172, v250, v251
	v_cvt_pk_bf16_f32 v173, v237, v196
	v_add_f32_e32 v197, v197, v237
	v_add_f32_e32 v207, v207, v196
	s_waitcnt lgkmcnt(7)
	v_mfma_f32_32x32x16_bf16 v[98:113], v[212:215], v[130:133], v[66:81]
	ds_read_b128 v[212:215], v206 offset:8800
	v_max3_f32 v178, v114, v115, v116
	s_waitcnt lgkmcnt(4)
	v_mfma_f32_32x32x16_bf16 v[98:113], v[216:219], v[134:137], v[98:113]
	v_max3_f32 v179, v117, v118, v119
	s_waitcnt lgkmcnt(2)
	v_mfma_f32_32x32x16_bf16 v[98:113], v[208:211], v[138:141], v[98:113]
	v_max3_f32 v178, v178, v120, v121
	s_waitcnt lgkmcnt(0)
	v_mfma_f32_32x32x16_bf16 v[98:113], v[212:215], v[142:145], v[98:113]
	v_max3_f32 v179, v179, v122, v123
	s_waitcnt lgkmcnt(0)
	s_barrier
	v_mfma_f32_32x32x16_bf16 v[34:49], v[220:223], v[170:173], v[34:49]
	ds_read_b128 v[220:223], v163 offset:17408
	ds_read_b128 v[208:211], v206 offset:35840
	v_max3_f32 v178, v178, v124, v125
	v_max3_f32 v179, v179, v126, v127
	v_max3_f32 v178, v178, v128, v129
	v_mfma_f32_32x32x16_bf16 v[18:33], v[224:227], v[170:173], v[18:33]
	ds_read_b128 v[224:227], v163 offset:22016
	ds_read_b128 v[212:215], v206 offset:35872
	v_max3_f32 v179, v179, v98, v99
	v_max3_f32 v178, v178, v100, v101
	v_max3_f32 v179, v179, v102, v103
	v_max3_f32 v178, v178, v104, v105
	v_mfma_f32_32x32x16_bf16 v[2:17], v[228:231], v[170:173], v[2:17]
	ds_read_b128 v[228:231], v163 offset:26624
	ds_read_b128 v[216:219], v206 offset:35904
	v_max3_f32 v179, v179, v106, v107
	v_max3_f32 v178, v178, v108, v109
	v_max3_f32 v179, v179, v110, v111
	v_max3_f32 v178, v178, v112, v113
	v_max_f32_e32 v178, v178, v179
	v_mov_b32_e32 v179, v178
	s_nop 1
	v_permlane32_swap_b32_e32 v178, v179
	v_max_f32_e32 v178, v178, v179
	v_cmp_lt_f32_e32 vcc, 0x41000000, v178
	v_mfma_f32_32x32x16_bf16 v[50:65], v[238:241], v[170:173], v[50:65]
	ds_read_b128 v[238:241], v163 offset:31232
	s_cbranch_vccnz .Lat_rare_2
